# ssd_conv: channel-block-major descending job order (reads the oldest still-cached XBCP columns first; adjacent token blocks per channel row written together)
# speedup vs baseline: 1.0098x; 1.0008x over previous
; __device__ __forceinline__ void ssd_conv_phase(Frame& F, int j, bool skip_ctx_c) {
;     ...
;     for (int job = gw; job < NTB * NCB; job += NGW) {
;         const int cb = job % NCB, tb = job / NCB;
;         const int rb = tb * 64;
;         if (skip_ctx_c && rb >= MLAT && cb >= 80) continue;
;         int seq0, T, sb;
;         if (rb < MLAT) { sb = rb >> 11; seq0 = sb << 11; T = LSEQ; } else { sb = (rb - MLAT) >> 8; seq0 = MLAT + (sb << 8); T = LCTX; }
;         const int tl = rb - seq0 + tq * 8;
.LBB0_381:
	s_lshr_b32 s4, s7, 5
	s_mul_i32 s4, s4, 0xe38f
	s_lshr_b32 s4, s4, 19
	s_mul_i32 s5, s4, 0xfffffee0
	s_add_i32 s40, s7, s5
	s_sub_i32 s15, 95, s4
	s_cmpk_gt_i32 s40, 0xff
	s_cselect_b64 s[4:5], -1, 0
	s_cmpk_gt_i32 s15, 0x4f
	s_cselect_b64 s[36:37], -1, 0
	s_and_b64 s[4:5], s[4:5], s[36:37]
	s_and_b64 s[4:5], s[28:29], s[4:5]
	s_and_b64 vcc, exec, s[4:5]
	s_cbranch_vccnz .LBB0_380
	s_lshl_b32 s39, s40, 6
	s_cmpk_lt_i32 s40, 0x100
	s_cselect_b64 s[36:37], -1, 0
	s_cmpk_gt_i32 s40, 0xff
	s_mov_b64 s[4:5], -1
	s_cbranch_scc0 .LBB0_384
	s_add_i32 s4, s39, 0xffffc000
	s_lshr_b32 s38, s4, 8
	s_and_b32 s4, s4, 0xffffff00
	s_add_i32 s26, s4, 0x4000
	s_mov_b64 s[4:5], 0

;     __device__ __forceinline__ const char* a(const pg8::Unit& u) const { return (const char*)ws + aoff + (size_t)u.pm * 256 * K_ * 2 + (u.kq < 0 ? 0 : u.kq * (K_ / 4) * 2); }
;     __device__ __forceinline__ const char* b(const pg8::Unit& u) const { return (const char*)ws + boff + (size_t)u.pn * 256 * K_ * 2 + (u.kq < 0 ? 0 : u.kq * (K_ / 4) * 2); }
;     __device__ __forceinline__ const char* a(const pg8::Unit& u) const { return (const char*)ws + WS_A + (size_t)u.pm * 256 * D * 2; }
;     __device__ __forceinline__ const char* b(const pg8::Unit& u) const { return (const char*)ws + boff + (size_t)u.pn * 256 * D * 2; }
;     __device__ __forceinline__ const char* a(const pg8::Unit& u) const { return (const char*)ws + WS_A + (size_t)u.pm * 256 * D * 2; }
;     __device__ __forceinline__ const char* b(const pg8::Unit& u) const { return (const char*)ws + boff + (size_t)u.pn * 256 * D * 2; }
;     __device__ __forceinline__ const char* a(const pg8::Unit& u) const { return (const char*)ws + WS_W1 + (size_t)(u.pm & 1) * 256 * 256 * 2; }
;     __device__ __forceinline__ const char* b(const pg8::Unit& u) const { return (const char*)ws + WS_A + ((size_t)u.pn * 256 * D + (size_t)(u.pm >> 1) * 256) * 2; }
; __device__ __forceinline__ void ssd_conv_phase(Frame& F, int j, bool skip_ctx_c) {
;     ...
;         const int c0 = cb * 64 + cq * 8;
;         float w0[8], w1[8], w2[8], bi[8];
;         { const f32x4* p = (const f32x4*)(cw + c0); const f32x4 a = p[0], b = p[1]; w0[0] = a.x; w0[1] = a.y; w0[2] = a.z; w0[3] = a.w; w0[4] = b.x; w0[5] = b.y; w0[6] = b.z; w0[7] = b.w; }
;         { const f32x4* p = (const f32x4*)(cw + XBC + c0); const f32x4 a = p[0], b = p[1]; w1[0] = a.x; w1[1] = a.y; w1[2] = a.z; w1[3] = a.w; w1[4] = b.x; w1[5] = b.y; w1[6] = b.z; w1[7] = b.w; }
;         { const f32x4* p = (const f32x4*)(cw + 2 * XBC + c0); const f32x4 a = p[0], b = p[1]; w2[0] = a.x; w2[1] = a.y; w2[2] = a.z; w2[3] = a.w; w2[4] = b.x; w2[5] = b.y; w2[6] = b.z; w2[7] = b.w; }
;         { const f32x4* p = (const f32x4*)(cb_ + c0); const f32x4 a = p[0], b = p[1]; bi[0] = a.x; bi[1] = a.y; bi[2] = a.z; bi[3] = a.w; bi[4] = b.x; bi[5] = b.y; bi[6] = b.z; bi[7] = b.w; }
;         u32x4 raw[10];
; #pragma unroll
;         for (int i = 0; i < 10; ++i) { const int tt = tl - 1 + i; raw[i] = (tt >= 0 && tt < T) ? *(const u32x4*)(pre + (size_t)(seq0 + tt) * XBC + c0) : (u32x4){0u, 0u, 0u, 0u}; }
.LBB0_386:
	s_lshl_b32 s100, s7, 6
	s_lshl_b32 s101, s15, 6
	v_subrev_u32_e32 v72, s100, v93
	v_add_u32_e32 v72, s101, v72
	v_ashrrev_i32_e32 v73, 31, v72
	v_lshlrev_b64 v[12:13], 2, v[72:73]
	v_lshl_add_u64 v[4:5], s[0:1], 0, v[12:13]
	v_lshl_add_u64 v[8:9], s[30:31], 0, v[12:13]
	v_lshl_add_u64 v[14:15], s[34:35], 0, v[12:13]
	v_lshl_add_u64 v[16:17], s[10:11], 0, v[12:13]
	global_load_dwordx4 v[0:3], v[4:5], off offset:16
	global_load_dwordx4 v[56:59], v[4:5], off
	s_nop 0
	global_load_dwordx4 v[4:7], v[8:9], off offset:16
	global_load_dwordx4 v[52:55], v[8:9], off
	s_nop 0
	global_load_dwordx4 v[8:11], v[14:15], off offset:16
	global_load_dwordx4 v[48:51], v[14:15], off
	s_nop 0
	global_load_dwordx4 v[12:15], v[16:17], off offset:16
	global_load_dwordx4 v[60:63], v[16:17], off
	s_sub_i32 s4, s39, s26
	v_add_u32_e32 v74, s4, v92
	v_readlane_b32 s4, v252, 62
	v_add_u32_e32 v17, -1, v74
	v_readlane_b32 s5, v252, 63
	v_cmp_gt_u32_e32 vcc, s14, v17
	v_mov_b32_e32 v16, 0
	v_lshl_add_u64 v[78:79], v[72:73], 1, s[4:5]
	v_mov_b32_e32 v20, 0
	v_mov_b32_e32 v21, 0
	v_mov_b32_e32 v22, 0
	v_mov_b32_e32 v23, 0
	s_and_saveexec_b64 s[4:5], vcc
	s_cbranch_execz .LBB0_388
	v_add_u32_e32 v17, s26, v17
	s_movk_i32 s40, 0x3000
	v_mad_i64_i32 v[18:19], s[40:41], v17, s40, v[78:79]
	global_load_dwordx4 v[20:23], v[18:19], off
